# v88 + P2/P6 sample in-projection small_gemm K sections with coalesced loads and per-wave LDS transpose
# speedup vs baseline: 1.0147x; 1.0041x over previous
; template <class F>
; DI void small_gemm(LAS unsigned char* lds, const bf16_t* A, int lda, const bf16_t* Wt, int ldb, int K, int N, int tile0, int tstride, F f) {
;     ...
;         const bf16_t* ap = A + (size_t)r * lda + wid * kw + 8 * h;
;         const bf16_t* bp = Wt + (size_t)(n0 + r) * ldb + wid * kw + 8 * h;
; #pragma unroll 8
;         for (int ks = 0; ks < kw; ks += 16) {
;             const bf16x8 a = *(const bf16x8*)(ap + ks), b = *(const bf16x8*)(bp + ks);
;             acc = __builtin_amdgcn_mfma_f32_32x32x16_bf16(a, b, acc, 0, 0, 0);
;         }
; #pragma unroll
;         for (int i = 0; i < 16; ++i) red[wid * 1024 + i * 64 + lane] = acc[i];
;         __syncthreads();
.LBB0_236:
	s_lshl_b32 s0, s42, 5
	v_or_b32_e32 v22, s0, v25
	v_ashrrev_i32_e32 v23, 31, v22
	v_lshlrev_b64 v[4:5], 11, v[22:23]
	v_lshl_add_u64 v[50:51], v[18:19], 0, v[4:5]
	v_and_b32_e32 v167, 63, v226
	v_lshrrev_b32_e32 v168, 4, v167
	v_and_b32_e32 v164, 15, v167
	v_lshlrev_b32_e32 v164, 4, v164
	v_mul_u32_u24_e32 v165, 0x110, v168
	v_add_u32_e32 v165, v165, v164
	v_lshl_or_b32 v164, v168, 11, v164
	v_lshrrev_b32_e32 v168, 6, v226
	v_and_b32_e32 v166, 31, v167
	v_mul_u32_u24_e32 v166, 0x110, v166
	v_lshrrev_b32_e32 v167, 5, v167
	v_lshl_add_u32 v166, v167, 4, v166
	s_nop 1
	v_readfirstlane_b32 s60, v168
	v_readfirstlane_b32 s56, v16
	v_readfirstlane_b32 s57, v17
	v_readfirstlane_b32 s58, v50
	v_readfirstlane_b32 s59, v51
	s_nop 4
	s_mul_i32 s60, s60, 0x4400
	v_add_u32_e32 v165, s60, v165
	v_add_u32_e32 v166, s60, v166
	global_load_dwordx4 v[32:35], v164, s[56:57]
	global_load_dwordx4 v[36:39], v164, s[58:59]
	s_add_u32 s56, s56, 0x2000
	s_addc_u32 s57, s57, 0
	s_add_u32 s58, s58, 0x2000
	s_addc_u32 s59, s59, 0
	global_load_dwordx4 v[40:43], v164, s[56:57]
	global_load_dwordx4 v[44:47], v164, s[58:59]
	s_add_u32 s56, s56, 0x2000
	s_addc_u32 s57, s57, 0
	s_add_u32 s58, s58, 0x2000
	s_addc_u32 s59, s59, 0
	global_load_dwordx4 v[48:51], v164, s[56:57]
	global_load_dwordx4 v[52:55], v164, s[58:59]
	s_add_u32 s56, s56, 0x2000
	s_addc_u32 s57, s57, 0
	s_add_u32 s58, s58, 0x2000
	s_addc_u32 s59, s59, 0
	global_load_dwordx4 v[56:59], v164, s[56:57]
	global_load_dwordx4 v[60:63], v164, s[58:59]
	s_add_u32 s56, s56, 0x2000
	s_addc_u32 s57, s57, 0
	s_add_u32 s58, s58, 0x2000
	s_addc_u32 s59, s59, 0
	global_load_dwordx4 v[64:67], v164, s[56:57]
	global_load_dwordx4 v[68:71], v164, s[58:59]
	s_add_u32 s56, s56, 0x2000
	s_addc_u32 s57, s57, 0
	s_add_u32 s58, s58, 0x2000
	s_addc_u32 s59, s59, 0
	global_load_dwordx4 v[72:75], v164, s[56:57]
	global_load_dwordx4 v[76:79], v164, s[58:59]
	s_add_u32 s56, s56, 0x2000
	s_addc_u32 s57, s57, 0
	s_add_u32 s58, s58, 0x2000
	s_addc_u32 s59, s59, 0
	global_load_dwordx4 v[80:83], v164, s[56:57]
	global_load_dwordx4 v[84:87], v164, s[58:59]
	s_add_u32 s56, s56, 0x2000
	s_addc_u32 s57, s57, 0
	s_add_u32 s58, s58, 0x2000
	s_addc_u32 s59, s59, 0
	global_load_dwordx4 v[88:91], v164, s[56:57]
	global_load_dwordx4 v[92:95], v164, s[58:59]
	s_waitcnt vmcnt(14)
	ds_write_b128 v165, v[32:35]
	ds_write_b128 v165, v[36:39] offset:8704
	s_waitcnt vmcnt(12)
	ds_write_b128 v165, v[40:43] offset:1088
	ds_write_b128 v165, v[44:47] offset:9792
	s_waitcnt vmcnt(10)
	ds_write_b128 v165, v[48:51] offset:2176
	ds_write_b128 v165, v[52:55] offset:10880
	s_waitcnt vmcnt(8)
	ds_write_b128 v165, v[56:59] offset:3264
	ds_write_b128 v165, v[60:63] offset:11968
	s_waitcnt vmcnt(6)
	ds_write_b128 v165, v[64:67] offset:4352
	ds_write_b128 v165, v[68:71] offset:13056
	s_waitcnt vmcnt(4)
	ds_write_b128 v165, v[72:75] offset:5440
	ds_write_b128 v165, v[76:79] offset:14144
	s_waitcnt vmcnt(2)
	ds_write_b128 v165, v[80:83] offset:6528
	ds_write_b128 v165, v[84:87] offset:15232
	s_waitcnt vmcnt(0)
	ds_write_b128 v165, v[88:91] offset:7616
	ds_write_b128 v165, v[92:95] offset:16320
	s_waitcnt lgkmcnt(0)
	ds_read_b128 v[100:103], v166
	ds_read_b128 v[104:107], v166 offset:8704
	ds_read_b128 v[108:111], v166 offset:32
	ds_read_b128 v[112:115], v166 offset:8736
	ds_read_b128 v[116:119], v166 offset:64
	ds_read_b128 v[120:123], v166 offset:8768
	ds_read_b128 v[124:127], v166 offset:96
	ds_read_b128 v[128:131], v166 offset:8800
	ds_read_b128 v[132:135], v166 offset:128
	ds_read_b128 v[136:139], v166 offset:8832
	ds_read_b128 v[140:143], v166 offset:160
	ds_read_b128 v[144:147], v166 offset:8864
	ds_read_b128 v[148:151], v166 offset:192
	ds_read_b128 v[152:155], v166 offset:8896
	ds_read_b128 v[156:159], v166 offset:224
	ds_read_b128 v[160:163], v166 offset:8928
	s_waitcnt lgkmcnt(14)
	v_mfma_f32_32x32x16_bf16 v[0:15], v[100:103], v[104:107], 0
	s_waitcnt lgkmcnt(12)
	v_mfma_f32_32x32x16_bf16 v[0:15], v[108:111], v[112:115], v[0:15]
	s_waitcnt lgkmcnt(10)
	v_mfma_f32_32x32x16_bf16 v[0:15], v[116:119], v[120:123], v[0:15]
	s_waitcnt lgkmcnt(8)
	v_mfma_f32_32x32x16_bf16 v[0:15], v[124:127], v[128:131], v[0:15]
	s_waitcnt lgkmcnt(6)
	v_mfma_f32_32x32x16_bf16 v[0:15], v[132:135], v[136:139], v[0:15]
	s_waitcnt lgkmcnt(4)
	v_mfma_f32_32x32x16_bf16 v[0:15], v[140:143], v[144:147], v[0:15]
	s_waitcnt lgkmcnt(2)
	v_mfma_f32_32x32x16_bf16 v[0:15], v[148:151], v[152:155], v[0:15]
	s_waitcnt lgkmcnt(0)
	v_mfma_f32_32x32x16_bf16 v[0:15], v[156:159], v[160:163], v[0:15]
	s_barrier
	s_nop 11
	ds_write2st64_b32 v28, v0, v1 offset1:1
	ds_write2st64_b32 v28, v2, v3 offset0:2 offset1:3
	ds_write2st64_b32 v28, v4, v5 offset0:4 offset1:5
	ds_write2st64_b32 v28, v6, v7 offset0:6 offset1:7
	ds_write2st64_b32 v28, v8, v9 offset0:8 offset1:9
	ds_write2st64_b32 v28, v10, v11 offset0:10 offset1:11
	ds_write2st64_b32 v28, v12, v13 offset0:12 offset1:13
	ds_write2st64_b32 v28, v14, v15 offset0:14 offset1:15
	s_waitcnt lgkmcnt(0)
	s_barrier
	s_and_saveexec_b64 s[8:9], vcc
	s_cbranch_execz .LBB0_235
	s_lshr_b32 s0, s0, 6
	s_and_b32 s43, s0, 2
	s_lshl_b32 s0, s42, 3
	v_lshrrev_b32_e32 v0, 1, v22
	s_and_b32 s4, s0, 0xffffffc0
	v_and_b32_e32 v0, 60, v0
	v_cmp_lt_i32_e64 s[0:1], s3, v22
	v_or3_b32 v6, v26, v0, s4
	s_mov_b64 s[10:11], 0
	v_mov_b32_e32 v7, v27
	v_mov_b32_e32 v8, v24
	s_branch .LBB0_239

; template <class F>
; DI void small_gemm(LAS unsigned char* lds, const bf16_t* A, int lda, const bf16_t* Wt, int ldb, int K, int N, int tile0, int tstride, F f) {
;     ...
;         const bf16_t* ap = A + (size_t)r * lda + wid * kw + 8 * h;
;         const bf16_t* bp = Wt + (size_t)(n0 + r) * ldb + wid * kw + 8 * h;
; #pragma unroll 8
;         for (int ks = 0; ks < kw; ks += 16) {
;             const bf16x8 a = *(const bf16x8*)(ap + ks), b = *(const bf16x8*)(bp + ks);
;             acc = __builtin_amdgcn_mfma_f32_32x32x16_bf16(a, b, acc, 0, 0, 0);
;         }
; #pragma unroll
;         for (int i = 0; i < 16; ++i) red[wid * 1024 + i * 64 + lane] = acc[i];
;         __syncthreads();
.LBB0_1607:
	v_lshl_or_b32 v20, s18, 5, v23
	v_ashrrev_i32_e32 v21, 31, v20
	v_lshlrev_b64 v[4:5], 11, v[20:21]
	v_lshl_add_u64 v[46:47], v[18:19], 0, v[4:5]
	v_and_b32_e32 v167, 63, v226
	v_lshrrev_b32_e32 v168, 4, v167
	v_and_b32_e32 v164, 15, v167
	v_lshlrev_b32_e32 v164, 4, v164
	v_mul_u32_u24_e32 v165, 0x110, v168
	v_add_u32_e32 v165, v165, v164
	v_lshl_or_b32 v164, v168, 11, v164
	v_lshrrev_b32_e32 v168, 6, v226
	v_and_b32_e32 v166, 31, v167
	v_mul_u32_u24_e32 v166, 0x110, v166
	v_lshrrev_b32_e32 v167, 5, v167
	v_lshl_add_u32 v166, v167, 4, v166
	s_nop 1
	v_readfirstlane_b32 s60, v168
	v_readfirstlane_b32 s56, v16
	v_readfirstlane_b32 s57, v17
	v_readfirstlane_b32 s58, v46
	v_readfirstlane_b32 s59, v47
	s_nop 4
	s_mul_i32 s60, s60, 0x4400
	v_add_u32_e32 v165, s60, v165
	v_add_u32_e32 v166, s60, v166
	global_load_dwordx4 v[32:35], v164, s[56:57]
	global_load_dwordx4 v[36:39], v164, s[58:59]
	s_add_u32 s56, s56, 0x2000
	s_addc_u32 s57, s57, 0
	s_add_u32 s58, s58, 0x2000
	s_addc_u32 s59, s59, 0
	global_load_dwordx4 v[40:43], v164, s[56:57]
	global_load_dwordx4 v[44:47], v164, s[58:59]
	s_add_u32 s56, s56, 0x2000
	s_addc_u32 s57, s57, 0
	s_add_u32 s58, s58, 0x2000
	s_addc_u32 s59, s59, 0
	global_load_dwordx4 v[48:51], v164, s[56:57]
	global_load_dwordx4 v[52:55], v164, s[58:59]
	s_add_u32 s56, s56, 0x2000
	s_addc_u32 s57, s57, 0
	s_add_u32 s58, s58, 0x2000
	s_addc_u32 s59, s59, 0
	global_load_dwordx4 v[56:59], v164, s[56:57]
	global_load_dwordx4 v[60:63], v164, s[58:59]
	s_add_u32 s56, s56, 0x2000
	s_addc_u32 s57, s57, 0
	s_add_u32 s58, s58, 0x2000
	s_addc_u32 s59, s59, 0
	global_load_dwordx4 v[64:67], v164, s[56:57]
	global_load_dwordx4 v[68:71], v164, s[58:59]
	s_add_u32 s56, s56, 0x2000
	s_addc_u32 s57, s57, 0
	s_add_u32 s58, s58, 0x2000
	s_addc_u32 s59, s59, 0
	global_load_dwordx4 v[72:75], v164, s[56:57]
	global_load_dwordx4 v[76:79], v164, s[58:59]
	s_add_u32 s56, s56, 0x2000
	s_addc_u32 s57, s57, 0
	s_add_u32 s58, s58, 0x2000
	s_addc_u32 s59, s59, 0
	global_load_dwordx4 v[80:83], v164, s[56:57]
	global_load_dwordx4 v[84:87], v164, s[58:59]
	s_add_u32 s56, s56, 0x2000
	s_addc_u32 s57, s57, 0
	s_add_u32 s58, s58, 0x2000
	s_addc_u32 s59, s59, 0
	global_load_dwordx4 v[88:91], v164, s[56:57]
	global_load_dwordx4 v[92:95], v164, s[58:59]
	s_waitcnt vmcnt(14)
	ds_write_b128 v165, v[32:35]
	ds_write_b128 v165, v[36:39] offset:8704
	s_waitcnt vmcnt(12)
	ds_write_b128 v165, v[40:43] offset:1088
	ds_write_b128 v165, v[44:47] offset:9792
	s_waitcnt vmcnt(10)
	ds_write_b128 v165, v[48:51] offset:2176
	ds_write_b128 v165, v[52:55] offset:10880
	s_waitcnt vmcnt(8)
	ds_write_b128 v165, v[56:59] offset:3264
	ds_write_b128 v165, v[60:63] offset:11968
	s_waitcnt vmcnt(6)
	ds_write_b128 v165, v[64:67] offset:4352
	ds_write_b128 v165, v[68:71] offset:13056
	s_waitcnt vmcnt(4)
	ds_write_b128 v165, v[72:75] offset:5440
	ds_write_b128 v165, v[76:79] offset:14144
	s_waitcnt vmcnt(2)
	ds_write_b128 v165, v[80:83] offset:6528
	ds_write_b128 v165, v[84:87] offset:15232
	s_waitcnt vmcnt(0)
	ds_write_b128 v165, v[88:91] offset:7616
	ds_write_b128 v165, v[92:95] offset:16320
	s_waitcnt lgkmcnt(0)
	ds_read_b128 v[100:103], v166
	ds_read_b128 v[104:107], v166 offset:8704
	ds_read_b128 v[108:111], v166 offset:32
	ds_read_b128 v[112:115], v166 offset:8736
	ds_read_b128 v[116:119], v166 offset:64
	ds_read_b128 v[120:123], v166 offset:8768
	ds_read_b128 v[124:127], v166 offset:96
	ds_read_b128 v[128:131], v166 offset:8800
	ds_read_b128 v[132:135], v166 offset:128
	ds_read_b128 v[136:139], v166 offset:8832
	ds_read_b128 v[140:143], v166 offset:160
	ds_read_b128 v[144:147], v166 offset:8864
	ds_read_b128 v[148:151], v166 offset:192
	ds_read_b128 v[152:155], v166 offset:8896
	ds_read_b128 v[156:159], v166 offset:224
	ds_read_b128 v[160:163], v166 offset:8928
	s_waitcnt lgkmcnt(14)
	v_mfma_f32_32x32x16_bf16 v[0:15], v[100:103], v[104:107], 0
	s_waitcnt lgkmcnt(12)
	v_mfma_f32_32x32x16_bf16 v[0:15], v[108:111], v[112:115], v[0:15]
	s_waitcnt lgkmcnt(10)
	v_mfma_f32_32x32x16_bf16 v[0:15], v[116:119], v[120:123], v[0:15]
	s_waitcnt lgkmcnt(8)
	v_mfma_f32_32x32x16_bf16 v[0:15], v[124:127], v[128:131], v[0:15]
	s_waitcnt lgkmcnt(6)
	v_mfma_f32_32x32x16_bf16 v[0:15], v[132:135], v[136:139], v[0:15]
	s_waitcnt lgkmcnt(4)
	v_mfma_f32_32x32x16_bf16 v[0:15], v[140:143], v[144:147], v[0:15]
	s_waitcnt lgkmcnt(2)
	v_mfma_f32_32x32x16_bf16 v[0:15], v[148:151], v[152:155], v[0:15]
	s_waitcnt lgkmcnt(0)
	v_mfma_f32_32x32x16_bf16 v[0:15], v[156:159], v[160:163], v[0:15]
	s_barrier
	s_nop 11
	ds_write2st64_b32 v25, v0, v1 offset1:1
	ds_write2st64_b32 v25, v2, v3 offset0:2 offset1:3
	ds_write2st64_b32 v25, v4, v5 offset0:4 offset1:5
	ds_write2st64_b32 v25, v6, v7 offset0:6 offset1:7
	ds_write2st64_b32 v25, v8, v9 offset0:8 offset1:9
	ds_write2st64_b32 v25, v10, v11 offset0:10 offset1:11
	ds_write2st64_b32 v25, v12, v13 offset0:12 offset1:13
	ds_write2st64_b32 v25, v14, v15 offset0:14 offset1:15
	s_waitcnt lgkmcnt(0)
	s_barrier
	s_and_saveexec_b64 s[8:9], s[6:7]
	s_cbranch_execz .LBB0_1606
	s_and_b32 s0, s18, 0x7ffffe0
	s_cmpk_lg_i32 s0, 0x60
	s_cselect_b64 s[10:11], -1, 0
	s_and_b32 s0, s18, 0x7ffff60
	s_cmp_eq_u32 s0, 32
	s_cselect_b64 s[0:1], -1, 0
	v_cndmask_b32_e64 v2, 0, 1, s[0:1]
	v_lshl_add_u64 v[0:1], v[20:21], 1, s[30:31]
	s_mov_b64 s[12:13], 0
	v_cmp_ne_u32_e64 s[0:1], 1, v2
	v_mov_b32_e32 v2, v24
	v_mov_b32_e32 v3, v22
	s_branch .LBB0_1610
